# P2: merged-tile stores as 2 dwordx4 (permlane16 swaps) instead of 4 dwordx2
# speedup vs baseline: 1.0380x; 1.0026x over previous
.LBB0_208:
	s_or_b64 exec, exec, s[0:1]
	v_readlane_b32 s0, v255, 19
	v_readlane_b32 s1, v255, 20
	s_and_b64 s[0:1], s[0:1], exec
	s_cselect_b32 s0, s96, s41
	s_lshl_b32 s0, s0, 7
	s_or_b32 s13, s0, s79
	v_add_u32_e32 v0, 0, v91
	v_or_b32_e32 v1, s13, v101
	s_waitcnt lgkmcnt(0)
	v_mad_u32_u24 v1, v1, s61, v0
	ds_read_b128 v[74:77], v1
	ds_read_b128 v[78:81], v1 offset:64
	s_and_b64 s[0:1], s[98:99], exec
	s_cselect_b32 s0, s96, s41
	s_lshl_b32 s14, s0, 7
	s_waitcnt vmcnt(11) lgkmcnt(1)
	v_mfma_f32_16x16x32_bf16 v[74:77], v[74:77], v[44:47], 0
	s_or_b32 s0, s77, s14
	v_or_b32_e32 v1, s0, v101
	s_and_b64 s[0:1], s[4:5], exec
	v_mad_u32_u24 v1, v1, s61, v0
	s_cselect_b32 s0, s96, s41
	s_waitcnt vmcnt(10) lgkmcnt(0)
	v_mfma_f32_16x16x32_bf16 v[74:77], v[78:81], v[40:43], v[74:77]
	ds_read_b128 v[78:81], v1
	ds_read_b128 v[82:85], v1 offset:64
	s_lshl_b32 s0, s0, 7
	s_or_b32 s11, s0, s36
	v_or_b32_e32 v1, s11, v101
	v_mad_u32_u24 v1, v1, s61, v0
	s_waitcnt lgkmcnt(1)
	v_mfma_f32_16x16x32_bf16 v[78:81], v[78:81], v[44:47], 0
	ds_read_b128 v[86:89], v1
	s_and_b64 s[0:1], s[26:27], exec
	s_cselect_b32 s0, s96, s41
	s_waitcnt lgkmcnt(1)
	v_mfma_f32_16x16x32_bf16 v[78:81], v[82:85], v[40:43], v[78:81]
	ds_read_b128 v[82:85], v1 offset:64
	s_lshl_b32 s12, s0, 7
	s_or_b32 s0, s72, s12
	s_waitcnt lgkmcnt(1)
	v_mfma_f32_16x16x32_bf16 v[86:89], v[86:89], v[44:47], 0
	v_or_b32_e32 v1, s0, v101
	s_and_b64 s[0:1], s[24:25], exec
	v_mad_u32_u24 v1, v1, s61, v0
	s_cselect_b32 s0, s96, s41
	s_waitcnt lgkmcnt(0)
	v_mfma_f32_16x16x32_bf16 v[82:85], v[82:85], v[40:43], v[86:89]
	s_nop 2
	ds_read_b128 v[86:89], v1
	ds_read_b128 v[106:109], v1 offset:64
	s_lshl_b32 s0, s0, 7
	s_or_b32 s9, s0, s43
	v_or_b32_e32 v1, s9, v101
	v_mad_u32_u24 v1, v1, s61, v0
	s_waitcnt lgkmcnt(1)
	v_mfma_f32_16x16x32_bf16 v[86:89], v[86:89], v[44:47], 0
	ds_read_b128 v[110:113], v1
	s_and_b64 s[0:1], s[28:29], exec
	s_cselect_b32 s0, s96, s41
	s_waitcnt lgkmcnt(1)
	v_mfma_f32_16x16x32_bf16 v[86:89], v[106:109], v[40:43], v[86:89]
	ds_read_b128 v[106:109], v1 offset:64
	s_lshl_b32 s10, s0, 7
	s_or_b32 s0, s47, s10
	s_waitcnt lgkmcnt(1)
	v_mfma_f32_16x16x32_bf16 v[110:113], v[110:113], v[44:47], 0
	v_or_b32_e32 v1, s0, v101
	s_and_b64 s[0:1], s[2:3], exec
	v_mad_u32_u24 v1, v1, s61, v0
	s_cselect_b32 s0, s96, s41
	s_waitcnt lgkmcnt(0)
	v_mfma_f32_16x16x32_bf16 v[106:109], v[106:109], v[40:43], v[110:113]
	s_nop 2
	ds_read_b128 v[110:113], v1
	ds_read_b128 v[114:117], v1 offset:64
	s_lshl_b32 s0, s0, 7
	s_or_b32 s7, s0, s49
	v_or_b32_e32 v1, s7, v101
	v_mad_u32_u24 v1, v1, s61, v0
	s_waitcnt lgkmcnt(1)
	v_mfma_f32_16x16x32_bf16 v[110:113], v[110:113], v[44:47], 0
	ds_read_b128 v[118:121], v1
	s_and_b64 s[0:1], s[30:31], exec
	s_cselect_b32 s0, s96, s41
	s_waitcnt lgkmcnt(1)
	v_mfma_f32_16x16x32_bf16 v[110:113], v[114:117], v[40:43], v[110:113]
	ds_read_b128 v[114:117], v1 offset:64
	s_lshl_b32 s8, s0, 7
	s_or_b32 s0, s76, s8
	s_waitcnt lgkmcnt(1)
	v_mfma_f32_16x16x32_bf16 v[118:121], v[118:121], v[44:47], 0
	v_or_b32_e32 v1, s0, v101
	s_and_b64 s[0:1], s[80:81], exec
	v_mad_u32_u24 v1, v1, s61, v0
	s_cselect_b32 s0, s96, s41
	s_waitcnt lgkmcnt(0)
	v_mfma_f32_16x16x32_bf16 v[114:117], v[114:117], v[40:43], v[118:121]
	s_nop 2
	ds_read_b128 v[118:121], v1
	ds_read_b128 v[122:125], v1 offset:64
	s_lshl_b32 s0, s0, 7
	s_or_b32 s6, s0, s73
	v_or_b32_e32 v1, s6, v101
	v_mad_u32_u24 v0, v1, s61, v0
	s_waitcnt lgkmcnt(1)
	v_mfma_f32_16x16x32_bf16 v[118:121], v[118:121], v[44:47], 0
	ds_read_b128 v[126:129], v0
	s_cmp_lg_u32 s54, 0
	s_cselect_b64 s[0:1], -1, 0
	s_waitcnt lgkmcnt(1)
	v_mfma_f32_16x16x32_bf16 v[118:121], v[122:125], v[40:43], v[118:121]
	ds_read_b128 v[122:125], v0 offset:64
	v_cmp_lt_i32_e32 vcc, s68, v105
	s_or_b64 s[16:17], s[0:1], vcc
	s_waitcnt lgkmcnt(1)
	v_mfma_f32_16x16x32_bf16 v[44:47], v[126:129], v[44:47], 0
	v_cmp_ge_u32_e32 vcc, v103, v101
	s_and_b64 vcc, s[16:17], vcc
	v_or_b32_e32 v0, 1, v105
	s_waitcnt lgkmcnt(0)
	v_mfma_f32_16x16x32_bf16 v[40:43], v[122:125], v[40:43], v[44:47]
	v_or_b32_e32 v1, 2, v105
	v_or_b32_e32 v2, 3, v105
	s_mov_b32 s15, 0xff800000
	v_cndmask_b32_e32 v45, v96, v74, vcc
	v_cmp_lt_i32_e32 vcc, s69, v105
	s_or_b64 s[16:17], s[0:1], vcc
	v_cmp_ge_i32_e32 vcc, v0, v90
	s_and_b64 vcc, s[16:17], vcc
	v_add_u32_e32 v44, 0x80, v90
	v_cndmask_b32_e32 v0, v96, v75, vcc
	v_cmp_lt_i32_e32 vcc, s68, v1
	s_or_b64 s[16:17], s[0:1], vcc
	v_cmp_ge_i32_e32 vcc, v1, v90
	s_and_b64 vcc, vcc, s[16:17]
	v_max3_f32 v46, v45, s15, v0
	v_cndmask_b32_e32 v1, v96, v76, vcc
	v_cmp_lt_i32_e32 vcc, s68, v2
	s_or_b64 s[16:17], s[0:1], vcc
	v_cmp_ge_i32_e32 vcc, v2, v90
	s_and_b64 vcc, vcc, s[16:17]
	v_and_b32_e32 v104, 24, v104
	v_cndmask_b32_e32 v47, v96, v77, vcc
	v_max3_f32 v2, v46, v1, v47
	v_or_b32_e32 v46, s71, v103
	v_cmp_lt_i32_e32 vcc, s68, v46
	s_or_b64 vcc, s[0:1], vcc
	v_or_b32_e32 v76, 2, v46
	v_cndmask_b32_e32 v74, v96, v78, vcc
	v_cmp_lt_i32_e32 vcc, s69, v46
	s_or_b64 vcc, s[0:1], vcc
	v_or_b32_e32 v46, 3, v46
	v_cndmask_b32_e32 v75, v96, v79, vcc
	v_cmp_lt_i32_e32 vcc, s68, v76
	s_or_b64 vcc, s[0:1], vcc
	v_or_b32_e32 v77, s74, v103
	v_cndmask_b32_e32 v76, v96, v80, vcc
	v_cmp_lt_i32_e32 vcc, s68, v46
	s_or_b64 vcc, s[0:1], vcc
	v_or_b32_e32 v80, 2, v77
	v_cndmask_b32_e32 v46, v96, v81, vcc
	v_cmp_lt_i32_e32 vcc, s68, v77
	s_or_b64 vcc, s[0:1], vcc
	v_or_b32_e32 v81, s37, v103
	v_cndmask_b32_e32 v78, v96, v82, vcc
	v_cmp_lt_i32_e32 vcc, s69, v77
	s_or_b64 vcc, s[0:1], vcc
	v_or_b32_e32 v77, 3, v77
	v_cndmask_b32_e32 v79, v96, v83, vcc
	v_cmp_lt_i32_e32 vcc, s68, v80
	s_or_b64 vcc, s[0:1], vcc
	v_or_b32_e32 v82, 2, v81
	v_cndmask_b32_e32 v80, v96, v84, vcc
	v_cmp_lt_i32_e32 vcc, s68, v77
	s_or_b64 vcc, s[0:1], vcc
	v_max3_f32 v2, v2, v74, v75
	v_cndmask_b32_e32 v77, v96, v85, vcc
	v_cmp_lt_i32_e32 vcc, s68, v81
	s_or_b64 vcc, s[0:1], vcc
	v_max3_f32 v2, v2, v76, v46
	v_cndmask_b32_e32 v90, v96, v86, vcc
	v_cmp_lt_i32_e32 vcc, s69, v81
	s_or_b64 vcc, s[0:1], vcc
	v_or_b32_e32 v81, 3, v81
	v_cndmask_b32_e32 v91, v96, v87, vcc
	v_cmp_lt_i32_e32 vcc, s68, v82
	s_or_b64 vcc, s[0:1], vcc
	v_max3_f32 v2, v2, v78, v79
	v_cndmask_b32_e32 v122, v96, v88, vcc
	v_cmp_lt_i32_e32 vcc, s68, v81
	s_or_b64 vcc, s[0:1], vcc
	v_or_b32_e32 v81, s42, v103
	v_cndmask_b32_e32 v123, v96, v89, vcc
	v_cmp_lt_i32_e32 vcc, s68, v81
	s_or_b64 vcc, s[0:1], vcc
	v_or_b32_e32 v82, 2, v81
	v_cndmask_b32_e32 v124, v96, v106, vcc
	v_cmp_lt_i32_e32 vcc, s69, v81
	s_or_b64 vcc, s[0:1], vcc
	v_or_b32_e32 v81, 3, v81
	v_cndmask_b32_e32 v125, v96, v107, vcc
	v_cmp_lt_i32_e32 vcc, s68, v82
	s_or_b64 vcc, s[0:1], vcc
	v_max3_f32 v2, v2, v80, v77
	v_cndmask_b32_e32 v126, v96, v108, vcc
	v_cmp_lt_i32_e32 vcc, s68, v81
	s_or_b64 vcc, s[0:1], vcc
	v_or_b32_e32 v81, s46, v103
	v_cndmask_b32_e32 v127, v96, v109, vcc
	v_cmp_lt_i32_e32 vcc, s68, v81
	s_or_b64 vcc, s[0:1], vcc
	v_or_b32_e32 v82, 2, v81
	v_cndmask_b32_e32 v128, v96, v110, vcc
	v_cmp_lt_i32_e32 vcc, s69, v81
	s_or_b64 vcc, s[0:1], vcc
	v_or_b32_e32 v81, 3, v81
	v_cndmask_b32_e32 v129, v96, v111, vcc
	v_cmp_lt_i32_e32 vcc, s68, v82
	s_or_b64 vcc, s[0:1], vcc
	v_max3_f32 v2, v2, v90, v91
	v_cndmask_b32_e32 v130, v96, v112, vcc
	v_cmp_lt_i32_e32 vcc, s68, v81
	s_or_b64 vcc, s[0:1], vcc
	v_or_b32_e32 v81, s48, v103
	v_cndmask_b32_e32 v131, v96, v113, vcc
	v_cmp_lt_i32_e32 vcc, s68, v81
	s_or_b64 vcc, s[0:1], vcc
	v_or_b32_e32 v82, 2, v81
	v_cndmask_b32_e32 v132, v96, v114, vcc
	v_cmp_lt_i32_e32 vcc, s69, v81
	s_or_b64 vcc, s[0:1], vcc
	v_or_b32_e32 v81, 3, v81
	v_cndmask_b32_e32 v115, v96, v115, vcc
	v_cmp_lt_i32_e32 vcc, s68, v82
	s_or_b64 vcc, s[0:1], vcc
	v_max3_f32 v2, v2, v122, v123
	v_cndmask_b32_e32 v133, v96, v116, vcc
	v_cmp_lt_i32_e32 vcc, s68, v81
	v_max3_f32 v2, v2, v124, v125
	s_or_b64 vcc, s[0:1], vcc
	v_or_b32_e32 v81, s62, v103
	v_max3_f32 v2, v2, v126, v127
	v_cndmask_b32_e32 v134, v96, v117, vcc
	v_cmp_lt_i32_e32 vcc, s68, v81
	v_max3_f32 v2, v2, v128, v129
	s_or_b64 vcc, s[0:1], vcc
	v_max3_f32 v2, v2, v130, v131
	v_cndmask_b32_e32 v112, v96, v118, vcc
	v_cmp_lt_i32_e32 vcc, s69, v81
	v_max3_f32 v2, v2, v132, v115
	s_or_b64 vcc, s[0:1], vcc
	v_max3_f32 v2, v2, v133, v134
	v_cndmask_b32_e32 v113, v96, v119, vcc
	v_max3_f32 v82, v2, v112, v113
	v_or_b32_e32 v2, 2, v81
	v_cmp_lt_i32_e32 vcc, s68, v2
	s_or_b64 vcc, s[0:1], vcc
	v_or_b32_e32 v2, 3, v81
	v_cndmask_b32_e32 v114, v96, v120, vcc
	v_cmp_lt_i32_e32 vcc, s68, v2
	s_or_b64 vcc, s[0:1], vcc
	v_lshrrev_b32_e32 v116, 2, v101
	v_cndmask_b32_e32 v2, v96, v121, vcc
	v_max3_f32 v81, v82, v114, v2
	v_or_b32_e32 v82, s67, v103
	v_cmp_lt_i32_e32 vcc, s68, v82
	s_or_b64 s[16:17], s[0:1], vcc
	v_cmp_le_i32_e32 vcc, v82, v44
	s_and_b64 vcc, s[16:17], vcc
	v_or_b32_e32 v116, v103, v116
	v_cndmask_b32_e32 v108, v96, v40, vcc
	v_cmp_lt_i32_e32 vcc, s69, v82
	s_or_b64 s[16:17], s[0:1], vcc
	v_cmp_lt_i32_e32 vcc, v82, v44
	s_and_b64 vcc, s[16:17], vcc
	v_mul_u32_u24_e32 v116, 0x90, v116
	v_cndmask_b32_e32 v109, v96, v41, vcc
	v_or_b32_e32 v41, 2, v82
	v_cmp_lt_i32_e32 vcc, s68, v41
	s_or_b64 s[16:17], s[0:1], vcc
	v_cmp_le_i32_e32 vcc, v41, v44
	s_and_b64 vcc, s[16:17], vcc
	v_or_b32_e32 v41, 3, v82
	v_cndmask_b32_e32 v110, v96, v42, vcc
	v_cmp_lt_i32_e32 vcc, s68, v41
	s_or_b64 s[0:1], s[0:1], vcc
	v_cmp_le_i32_e32 vcc, v41, v44
	v_and_b32_e32 v42, 64, v95
	s_and_b64 vcc, s[0:1], vcc
	v_xor_b32_e32 v41, 16, v95
	v_add_u32_e32 v42, 64, v42
	v_cndmask_b32_e32 v111, v96, v43, vcc
	v_cmp_lt_i32_e32 vcc, v41, v42
	v_max3_f32 v40, v81, v108, v109
	v_max3_f32 v40, v40, v110, v111
	v_cndmask_b32_e32 v41, v95, v41, vcc
	v_lshlrev_b32_e32 v105, 2, v41
	ds_bpermute_b32 v41, v105, v40
	s_or_b32 s0, s14, s50
	v_add3_u32 v104, 0, v116, v104
	s_mulk_i32 s13, 0x90
	s_mulk_i32 s0, 0x90
	s_waitcnt lgkmcnt(0)
	v_max_f32_e32 v41, v41, v41
	v_max_f32_e32 v40, v40, v41
	v_xor_b32_e32 v41, 32, v95
	v_cmp_lt_i32_e32 vcc, v41, v42
	s_mulk_i32 s11, 0x90
	s_mulk_i32 s9, 0x90
	v_cndmask_b32_e32 v41, v95, v41, vcc
	v_lshlrev_b32_e32 v106, 2, v41
	ds_bpermute_b32 v41, v106, v40
	s_mulk_i32 s7, 0x90
	s_mulk_i32 s6, 0x90
	s_waitcnt lgkmcnt(0)
	v_max_f32_e32 v41, v41, v41
	v_max_f32_e32 v40, v40, v41
	v_mul_f32_e32 v40, 0x3e38aa3b, v40
	v_max_f32_e32 v41, v53, v53
	v_max_f32_e32 v107, v40, v41
	v_fma_f32 v42, v74, s70, -v107
	v_fma_f32 v1, v1, s70, -v107
	v_exp_f32_e32 v82, v42
	v_fma_f32 v42, v75, s70, -v107
	v_exp_f32_e32 v88, v1
	v_fma_f32 v1, v47, s70, -v107
	v_exp_f32_e32 v83, v42
	v_fma_f32 v42, v76, s70, -v107
	v_exp_f32_e32 v89, v1
	v_exp_f32_e32 v84, v42
	v_fma_f32 v42, v46, s70, -v107
	v_fma_f32 v43, v80, s70, -v107
	v_exp_f32_e32 v85, v42
	v_exp_f32_e32 v80, v43
	v_fma_f32 v43, v77, s70, -v107
	v_exp_f32_e32 v81, v43
	v_fma_f32 v0, v0, s70, -v107
	v_exp_f32_e32 v87, v0
	v_pk_add_f32 v[0:1], v[88:89], 0 op_sel_hi:[1,0]
	v_fma_f32 v42, v78, s70, -v107
	v_exp_f32_e32 v74, v42
	v_fma_f32 v42, v79, s70, -v107
	v_pk_add_f32 v[0:1], v[84:85], v[0:1]
	v_exp_f32_e32 v75, v42
	v_pk_add_f32 v[42:43], v[80:81], v[0:1]
	v_fma_f32 v0, v90, s70, -v107
	v_exp_f32_e32 v76, v0
	v_fma_f32 v0, v91, s70, -v107
	v_exp_f32_e32 v77, v0
	v_fma_f32 v0, v122, s70, -v107
	v_exp_f32_e32 v78, v0
	v_fma_f32 v0, v123, s70, -v107
	v_fma_f32 v40, v45, s70, -v107
	v_exp_f32_e32 v79, v0
	v_fma_f32 v44, v126, s70, -v107
	v_fma_f32 v45, v127, s70, -v107
	v_exp_f32_e32 v44, v44
	v_exp_f32_e32 v45, v45
	v_exp_f32_e32 v86, v40
	v_pk_add_f32 v[42:43], v[78:79], v[42:43]
	v_fma_f32 v0, v124, s70, -v107
	v_fma_f32 v1, v125, s70, -v107
	v_pk_add_f32 v[46:47], v[44:45], v[42:43]
	v_fma_f32 v42, v130, s70, -v107
	v_add_u32_e32 v126, s13, v104
	v_add_u32_e32 v130, s0, v104
	v_pk_add_f32 v[40:41], v[86:87], 0 op_sel_hi:[1,0]
	v_exp_f32_e32 v0, v0
	v_exp_f32_e32 v1, v1
	ds_read_b64_tr_b16 v[116:117], v126 offset:36864
	ds_read_b64_tr_b16 v[118:119], v130 offset:36864
	v_pk_add_f32 v[40:41], v[82:83], v[40:41]
	v_fma_f32 v43, v131, s70, -v107
	v_pk_add_f32 v[40:41], v[74:75], v[40:41]
	s_or_b32 s0, s12, s51
	v_pk_add_f32 v[40:41], v[76:77], v[40:41]
	s_mulk_i32 s0, 0x90
	v_pk_add_f32 v[90:91], v[0:1], v[40:41]
	v_fma_f32 v40, v128, s70, -v107
	v_fma_f32 v41, v129, s70, -v107
	ds_read_b64_tr_b16 v[122:123], v130 offset:36896
	ds_read_b64_tr_b16 v[120:121], v126 offset:36896
	ds_read_b64_tr_b16 v[124:125], v126 offset:36928
	ds_read_b64_tr_b16 v[128:129], v126 offset:36960
	ds_read_b64_tr_b16 v[126:127], v130 offset:36928
	ds_read_b64_tr_b16 v[130:131], v130 offset:36960
	v_cvt_pk_bf16_f32 v86, v86, v87
	v_cvt_pk_bf16_f32 v87, v88, v89
	v_cvt_pk_bf16_f32 v88, v82, v83
	v_cvt_pk_bf16_f32 v89, v84, v85
	v_fma_f32 v83, v115, s70, -v107
	v_add_u32_e32 v115, s11, v104
	v_add_u32_e32 v138, s0, v104
	s_waitcnt lgkmcnt(6)
	v_mfma_f32_16x16x32_bf16 v[116:119], v[116:119], v[86:89], 0
	v_fma_f32 v82, v132, s70, -v107
	v_fma_f32 v84, v133, s70, -v107
	v_fma_f32 v85, v134, s70, -v107
	s_waitcnt lgkmcnt(4)
	v_mfma_f32_16x16x32_bf16 v[120:123], v[120:123], v[86:89], 0
	v_cvt_pk_bf16_f32 v74, v74, v75
	v_cvt_pk_bf16_f32 v75, v80, v81
	v_cvt_pk_bf16_f32 v76, v76, v77
	s_waitcnt lgkmcnt(1)
	v_mfma_f32_16x16x32_bf16 v[124:127], v[124:127], v[86:89], 0
	v_cvt_pk_bf16_f32 v77, v78, v79
	v_fma_f32 v112, v112, s70, -v107
	s_or_b32 s0, s10, s33
	s_waitcnt lgkmcnt(0)
	v_mfma_f32_16x16x32_bf16 v[86:89], v[128:131], v[86:89], 0
	ds_read_b64_tr_b16 v[128:129], v115 offset:36864
	ds_read_b64_tr_b16 v[130:131], v138 offset:36864
	ds_read_b64_tr_b16 v[80:81], v138 offset:36896
	ds_read_b64_tr_b16 v[78:79], v115 offset:36896
	ds_read_b64_tr_b16 v[132:133], v115 offset:36928
	ds_read_b64_tr_b16 v[136:137], v115 offset:36960
	ds_read_b64_tr_b16 v[134:135], v138 offset:36928
	ds_read_b64_tr_b16 v[138:139], v138 offset:36960
	v_exp_f32_e32 v140, v112
	v_fma_f32 v112, v113, s70, -v107
	s_mulk_i32 s0, 0x90
	s_waitcnt lgkmcnt(6)
	v_mfma_f32_16x16x32_bf16 v[116:119], v[128:131], v[74:77], v[116:119]
	v_exp_f32_e32 v141, v112
	v_fma_f32 v112, v114, s70, -v107
	v_exp_f32_e32 v40, v40
	s_waitcnt lgkmcnt(4)
	v_mfma_f32_16x16x32_bf16 v[78:81], v[78:81], v[74:77], v[120:123]
	v_exp_f32_e32 v41, v41
	v_exp_f32_e32 v42, v42
	v_exp_f32_e32 v43, v43
	s_waitcnt lgkmcnt(1)
	v_mfma_f32_16x16x32_bf16 v[120:123], v[132:135], v[74:77], v[124:127]
	v_exp_f32_e32 v132, v112
	v_exp_f32_e32 v82, v82
	v_exp_f32_e32 v83, v83
	s_waitcnt lgkmcnt(0)
	v_mfma_f32_16x16x32_bf16 v[74:77], v[136:139], v[74:77], v[86:89]
	v_add_f32_e64 v90, v40, v90
	v_add_f32_e64 v91, v41, v91
	v_pk_add_f32 v[46:47], v[42:43], v[46:47]
	v_exp_f32_e32 v84, v84
	v_cvt_pk_bf16_f32 v86, v0, v1
	v_add_u32_e32 v0, s9, v104
	v_add_u32_e32 v1, s0, v104
	ds_read_b64_tr_b16 v[112:113], v0 offset:36864
	ds_read_b64_tr_b16 v[114:115], v1 offset:36864
	v_cvt_pk_bf16_f32 v88, v40, v41
	v_cvt_pk_bf16_f32 v89, v42, v43
	ds_read_b64_tr_b16 v[42:43], v1 offset:36896
	ds_read_b64_tr_b16 v[40:41], v0 offset:36896
	ds_read_b64_tr_b16 v[124:125], v0 offset:36928
	ds_read_b64_tr_b16 v[128:129], v0 offset:36960
	ds_read_b64_tr_b16 v[126:127], v1 offset:36928
	ds_read_b64_tr_b16 v[130:131], v1 offset:36960
	s_or_b32 s0, s8, s35
	v_exp_f32_e32 v85, v85
	v_pk_add_f32 v[90:91], v[82:83], v[90:91]
	v_cvt_pk_bf16_f32 v87, v44, v45
	v_fma_f32 v0, v2, s70, -v107
	v_fma_f32 v2, v108, s70, -v107
	v_fma_f32 v44, v110, s70, -v107
	s_mulk_i32 s0, 0x90
	v_exp_f32_e32 v133, v0
	v_pk_add_f32 v[0:1], v[140:141], v[90:91]
	s_waitcnt lgkmcnt(4)
	v_mfma_f32_16x16x32_bf16 v[40:43], v[40:43], v[86:89], v[78:81]
	v_exp_f32_e32 v90, v2
	v_fma_f32 v2, v109, s70, -v107
	v_add_u32_e32 v45, s7, v104
	s_waitcnt lgkmcnt(1)
	v_mfma_f32_16x16x32_bf16 v[78:81], v[124:127], v[86:89], v[120:123]
	v_exp_f32_e32 v124, v44
	v_fma_f32 v44, v111, s70, -v107
	v_add_u32_e32 v91, s0, v104
	v_mfma_f32_16x16x32_bf16 v[112:115], v[112:115], v[86:89], v[116:119]
	v_exp_f32_e32 v125, v44
	v_pk_add_f32 v[46:47], v[84:85], v[46:47]
	s_and_b64 s[0:1], s[52:53], exec
	s_waitcnt lgkmcnt(0)
	v_mfma_f32_16x16x32_bf16 v[74:77], v[128:131], v[86:89], v[74:77]
	ds_read_b64_tr_b16 v[86:87], v45 offset:36864
	ds_read_b64_tr_b16 v[88:89], v91 offset:36864
	ds_read_b64_tr_b16 v[110:111], v91 offset:36896
	ds_read_b64_tr_b16 v[108:109], v45 offset:36896
	ds_read_b64_tr_b16 v[116:117], v45 offset:36928
	ds_read_b64_tr_b16 v[120:121], v45 offset:36960
	ds_read_b64_tr_b16 v[118:119], v91 offset:36928
	ds_read_b64_tr_b16 v[122:123], v91 offset:36960
	v_exp_f32_e32 v91, v2
	v_cvt_pk_bf16_f32 v82, v82, v83
	v_cvt_pk_bf16_f32 v83, v84, v85
	v_cvt_pk_bf16_f32 v84, v140, v141
	v_cvt_pk_bf16_f32 v85, v132, v133
	v_pk_add_f32 v[44:45], v[132:133], v[46:47]
	s_cselect_b32 s0, s96, s41
	s_waitcnt lgkmcnt(4)
	v_mfma_f32_16x16x32_bf16 v[40:43], v[108:111], v[82:85], v[40:43]
	v_add_f32_e64 v108, v124, v44
	v_add_f32_e64 v109, v125, v45
	v_pk_add_f32 v[0:1], v[90:91], v[0:1]
	s_lshl_b32 s0, s0, 7
	v_pk_mov_b32 v[110:111], v[0:1], v[108:109] op_sel:[1,0]
	v_mov_b32_e32 v1, v109
	s_or_b32 s0, s0, s75
	v_pk_add_f32 v[0:1], v[110:111], v[0:1]
	s_mulk_i32 s0, 0x90
	s_waitcnt lgkmcnt(1)
	v_mfma_f32_16x16x32_bf16 v[44:47], v[116:119], v[82:85], v[78:81]
	v_add_f32_e32 v116, v0, v1
	v_cvt_pk_bf16_f32 v0, v90, v91
	v_add_u32_e32 v90, s6, v104
	v_add_u32_e32 v91, s0, v104
	ds_read_b64_tr_b16 v[78:79], v90 offset:36864
	ds_read_b64_tr_b16 v[80:81], v91 offset:36864
	v_mfma_f32_16x16x32_bf16 v[86:89], v[86:89], v[82:85], v[112:115]
	v_cvt_pk_bf16_f32 v1, v124, v125
	v_mov_b32_e32 v2, v3
	s_waitcnt vmcnt(0)
	v_permlane16_swap_b32_e32 v238, v240
	v_permlane16_swap_b32_e32 v239, v241
	v_permlane16_swap_b32_e32 v242, v244
	v_permlane16_swap_b32_e32 v243, v245
	v_permlane16_swap_b32_e32 v246, v248
	v_permlane16_swap_b32_e32 v247, v249
	v_permlane16_swap_b32_e32 v250, v252
	v_permlane16_swap_b32_e32 v251, v253
	v_permlane16_swap_b32_e32 v154, v156
	v_permlane16_swap_b32_e32 v155, v157
	v_permlane16_swap_b32_e32 v216, v218
	v_permlane16_swap_b32_e32 v217, v219
	v_mov_b64_e32 v[68:69], v[238:239]
	v_mov_b64_e32 v[62:63], v[240:241]
	v_mov_b64_e32 v[56:57], v[242:243]
	v_mov_b64_e32 v[48:49], v[244:245]
	v_mov_b64_e32 v[70:71], v[246:247]
	v_mov_b64_e32 v[64:65], v[248:249]
	v_mov_b64_e32 v[58:59], v[250:251]
	v_mov_b64_e32 v[50:51], v[252:253]
	v_mov_b64_e32 v[72:73], v[154:155]
	v_mov_b64_e32 v[66:67], v[156:157]
	v_mov_b64_e32 v[60:61], v[216:217]
	v_mov_b64_e32 v[54:55], v[218:219]
	v_and_b32_e32 v104, 0xffff0000, v70
	s_waitcnt lgkmcnt(2)
	v_mfma_f32_16x16x32_bf16 v[74:77], v[120:123], v[82:85], v[74:77]
	ds_read_b64_tr_b16 v[84:85], v91 offset:36896
	ds_read_b64_tr_b16 v[82:83], v90 offset:36896
	ds_read_b64_tr_b16 v[108:109], v90 offset:36928
	ds_read_b64_tr_b16 v[112:113], v90 offset:36960
	ds_read_b64_tr_b16 v[110:111], v91 offset:36928
	ds_read_b64_tr_b16 v[114:115], v91 offset:36960
	v_lshlrev_b32_e32 v90, 16, v70
	v_mul_f32_e32 v90, 0xbfb8aa3b, v90
	s_waitcnt lgkmcnt(6)
	v_mfma_f32_16x16x32_bf16 v[78:81], v[78:81], v[0:3], v[86:89]
	v_exp_f32_e32 v90, v90
	s_add_i32 s40, s40, 1
	s_nop 0
	ds_bpermute_b32 v86, v105, v116
	s_waitcnt lgkmcnt(5)
	v_mfma_f32_16x16x32_bf16 v[82:85], v[82:85], v[0:3], v[40:43]
	v_lshlrev_b32_e32 v88, 16, v73
	v_and_b32_e32 v89, 0xffff0000, v73
	v_lshlrev_b32_e32 v105, 16, v71
	s_waitcnt lgkmcnt(0)
	v_add_f32_e32 v40, v116, v86
	ds_bpermute_b32 v41, v106, v40
	v_sub_f32_e32 v42, v53, v107
	v_exp_f32_e32 v42, v42
	v_mfma_f32_16x16x32_bf16 v[44:47], v[108:111], v[0:3], v[44:47]
	v_and_b32_e32 v106, 0xffff0000, v69
	s_waitcnt lgkmcnt(0)
	v_add_f32_e32 v40, v40, v41
	v_add_f32_e32 v86, v42, v40
	v_mfma_f32_16x16x32_bf16 v[40:43], v[112:115], v[0:3], v[74:77]
	v_lshl_add_u32 v1, v103, 2, v102
	v_lshlrev_b32_e32 v2, 16, v68
	v_lshlrev_b32_e32 v102, 16, v69
	v_add_u32_e32 v74, s38, v101
	s_mov_b32 s100, 0x9f57000
	v_lshl_add_u64 v[22:23], v[20:21], 0, s[100:101]
	global_load_dwordx4 v[28:31], v[22:23], off offset:3072
	v_and_b32_e32 v101, 0xffff0000, v68
	v_lshlrev_b32_e32 v68, 16, v72
	v_and_b32_e32 v69, 0xffff0000, v72
	v_pk_mul_f32 v[72:73], v[68:69], v[68:69]
	v_mul_f32_e32 v2, 0xbfb8aa3b, v2
	v_fmamk_f32 v72, v72, 0xbdd2d3e7, v93
	v_mul_f32_e32 v72, v72, v68
	v_exp_f32_e32 v2, v2
	v_exp_f32_e32 v91, v72
	v_mul_f32_e32 v72, 0xbfb8aa3b, v101
	v_fmamk_f32 v73, v73, 0xbdd2d3e7, v93
	v_and_b32_e32 v107, 0xffff0000, v71
	v_pk_mul_f32 v[70:71], v[88:89], v[88:89]
	v_exp_f32_e32 v101, v72
	v_mul_f32_e32 v72, 0xbfb8aa3b, v104
	v_mul_f32_e32 v73, v73, v69
	v_exp_f32_e32 v72, v72
	v_exp_f32_e32 v73, v73
	v_fmamk_f32 v70, v70, 0xbdd2d3e7, v93
	v_mul_f32_e32 v102, 0xbfb8aa3b, v102
	v_mul_f32_e32 v104, 0xbfb8aa3b, v105
	v_mul_f32_e32 v70, v70, v88
	v_exp_f32_e32 v102, v102
	v_exp_f32_e32 v104, v104
	v_exp_f32_e32 v105, v70
	v_mul_f32_e32 v70, 0xbfb8aa3b, v106
	v_fmamk_f32 v71, v71, 0xbdd2d3e7, v93
	v_add_f32_e32 v2, 1.0, v2
	v_pk_add_f32 v[90:91], v[90:91], 1.0 op_sel_hi:[1,0]
	v_exp_f32_e32 v109, v70
	v_mul_f32_e32 v70, 0xbfb8aa3b, v107
	v_mul_f32_e32 v71, v71, v89
	v_rcp_f32_e32 v106, v2
	v_mul_f32_e32 v2, v90, v91
	v_exp_f32_e32 v70, v70
	v_exp_f32_e32 v71, v71
	v_rcp_f32_e32 v90, v2
	v_add_f32_e32 v2, 1.0, v101
	v_pk_add_f32 v[72:73], v[72:73], 1.0 op_sel_hi:[1,0]
	v_rcp_f32_e32 v107, v2
	v_mul_f32_e32 v2, v72, v73
	v_ashrrev_i32_e32 v75, 31, v74
	v_rcp_f32_e32 v91, v2
	v_add_f32_e32 v2, 1.0, v102
	v_pk_add_f32 v[72:73], v[104:105], 1.0 op_sel_hi:[1,0]
	v_lshlrev_b64 v[74:75], 11, v[74:75]
	v_rcp_f32_e32 v108, v2
	v_mul_f32_e32 v2, v72, v73
	v_rcp_f32_e32 v0, v86
	v_lshl_add_u64 v[86:87], s[44:45], 0, v[74:75]
	ds_read_b128 v[74:77], v1
	v_rcp_f32_e32 v104, v2
	v_add_f32_e32 v2, 1.0, v109
	v_pk_add_f32 v[70:71], v[70:71], 1.0 op_sel_hi:[1,0]
	v_rcp_f32_e32 v109, v2
	v_mul_f32_e32 v2, v70, v71
	v_rcp_f32_e32 v105, v2
	ds_read_b128 v[70:73], v1 offset:64
	s_waitcnt lgkmcnt(1)
	v_pk_mul_f32 v[76:77], v[76:77], v[88:89]
	v_pk_mul_f32 v[68:69], v[74:75], v[68:69]
	v_pk_mul_f32 v[80:81], v[0:1], v[80:81] op_sel_hi:[0,1]
	v_pk_mul_f32 v[78:79], v[0:1], v[78:79] op_sel_hi:[0,1]
	v_pk_mul_f32 v[68:69], v[90:91], v[68:69]
	v_pk_mul_f32 v[74:75], v[104:105], v[76:77]
	v_pk_fma_f32 v[68:69], v[106:107], v[78:79], v[68:69]
	v_pk_fma_f32 v[74:75], v[108:109], v[80:81], v[74:75]
	v_lshlrev_b32_e32 v2, 1, v103
	v_cvt_pk_bf16_f32 v76, v68, v69
	v_cvt_pk_bf16_f32 v77, v74, v75
	v_lshl_add_u64 v[68:69], v[86:87], 0, v[2:3]
	v_bfe_u32 v158, v52, 4, 1
	v_mul_u32_u24_e32 v158, 24, v158
	v_mov_b32_e32 v159, 0
	v_lshl_add_u64 v[158:159], v[68:69], 0, v[158:159]
	v_mov_b64_e32 v[238:239], v[76:77]
	v_pk_mul_f32 v[74:75], v[0:1], v[84:85] op_sel_hi:[0,1]
	v_pk_mul_f32 v[76:77], v[0:1], v[82:83] op_sel_hi:[0,1]
	v_lshlrev_b32_e32 v2, 16, v62
	v_and_b32_e32 v82, 0xffff0000, v62
	v_lshlrev_b32_e32 v83, 16, v63
	v_and_b32_e32 v84, 0xffff0000, v63
	v_lshlrev_b32_e32 v62, 16, v66
	v_and_b32_e32 v63, 0xffff0000, v66
	v_pk_mul_f32 v[78:79], v[62:63], v[62:63]
	v_lshlrev_b32_e32 v80, 16, v64
	v_fmamk_f32 v78, v78, 0xbdd2d3e7, v93
	v_mul_f32_e32 v2, 0xbfb8aa3b, v2
	v_mul_f32_e32 v80, 0xbfb8aa3b, v80
	v_mul_f32_e32 v78, v78, v62
	v_and_b32_e32 v85, 0xffff0000, v64
	v_lshlrev_b32_e32 v86, 16, v65
	v_and_b32_e32 v87, 0xffff0000, v65
	s_mov_b32 s100, 0x9f5a000
	v_lshl_add_u64 v[24:25], v[20:21], 0, s[100:101]
	global_load_dwordx4 v[24:27], v[24:25], off offset:2048
	v_lshlrev_b32_e32 v64, 16, v67
	v_and_b32_e32 v65, 0xffff0000, v67
	v_exp_f32_e32 v2, v2
	v_exp_f32_e32 v80, v80
	v_exp_f32_e32 v81, v78
	v_mul_f32_e32 v78, 0xbfb8aa3b, v82
	v_fmamk_f32 v79, v79, 0xbdd2d3e7, v93
	v_pk_mul_f32 v[66:67], v[64:65], v[64:65]
	v_exp_f32_e32 v88, v78
	v_mul_f32_e32 v78, 0xbfb8aa3b, v85
	v_mul_f32_e32 v79, v79, v63
	v_exp_f32_e32 v78, v78
	v_exp_f32_e32 v79, v79
	v_mul_f32_e32 v82, 0xbfb8aa3b, v83
	v_fmamk_f32 v66, v66, 0xbdd2d3e7, v93
	v_exp_f32_e32 v89, v82
	v_mul_f32_e32 v82, 0xbfb8aa3b, v86
	v_mul_f32_e32 v66, v66, v64
	v_exp_f32_e32 v82, v82
	v_exp_f32_e32 v83, v66
	v_mul_f32_e32 v66, 0xbfb8aa3b, v84
	v_fmamk_f32 v67, v67, 0xbdd2d3e7, v93
	v_add_f32_e32 v2, 1.0, v2
	v_pk_add_f32 v[80:81], v[80:81], 1.0 op_sel_hi:[1,0]
	v_exp_f32_e32 v86, v66
	v_mul_f32_e32 v66, 0xbfb8aa3b, v87
	v_mul_f32_e32 v67, v67, v65
	v_rcp_f32_e32 v84, v2
	v_mul_f32_e32 v2, v80, v81
	v_exp_f32_e32 v66, v66
	v_exp_f32_e32 v67, v67
	v_rcp_f32_e32 v80, v2
	v_add_f32_e32 v2, 1.0, v88
	v_pk_add_f32 v[78:79], v[78:79], 1.0 op_sel_hi:[1,0]
	v_rcp_f32_e32 v85, v2
	v_mul_f32_e32 v2, v78, v79
	v_rcp_f32_e32 v81, v2
	v_add_f32_e32 v2, 1.0, v89
	v_pk_add_f32 v[82:83], v[82:83], 1.0 op_sel_hi:[1,0]
	v_rcp_f32_e32 v78, v2
	v_mul_f32_e32 v2, v82, v83
	v_rcp_f32_e32 v82, v2
	v_add_f32_e32 v2, 1.0, v86
	v_pk_add_f32 v[66:67], v[66:67], 1.0 op_sel_hi:[1,0]
	v_rcp_f32_e32 v79, v2
	v_mul_f32_e32 v2, v66, v67
	v_rcp_f32_e32 v83, v2
	s_waitcnt lgkmcnt(0)
	v_pk_mul_f32 v[64:65], v[72:73], v[64:65]
	v_lshlrev_b32_e32 v2, 16, v56
	v_and_b32_e32 v72, 0xffff0000, v56
	v_pk_mul_f32 v[64:65], v[82:83], v[64:65]
	v_lshlrev_b32_e32 v73, 16, v57
	v_pk_fma_f32 v[64:65], v[78:79], v[74:75], v[64:65]
	v_and_b32_e32 v74, 0xffff0000, v57
	v_lshlrev_b32_e32 v56, 16, v60
	v_and_b32_e32 v57, 0xffff0000, v60
	v_pk_mul_f32 v[66:67], v[0:1], v[46:47] op_sel_hi:[0,1]
	v_pk_mul_f32 v[46:47], v[56:57], v[56:57]
	v_pk_mul_f32 v[62:63], v[70:71], v[62:63]
	v_lshlrev_b32_e32 v75, 16, v58
	v_fmamk_f32 v46, v46, 0xbdd2d3e7, v93
	v_pk_mul_f32 v[62:63], v[80:81], v[62:63]
	v_mul_f32_e32 v2, 0xbfb8aa3b, v2
	v_mul_f32_e32 v60, 0xbfb8aa3b, v75
	v_mul_f32_e32 v46, v46, v56
	v_pk_fma_f32 v[62:63], v[84:85], v[76:77], v[62:63]
	v_and_b32_e32 v76, 0xffff0000, v58
	v_lshlrev_b32_e32 v77, 16, v59
	v_and_b32_e32 v78, 0xffff0000, v59
	v_lshlrev_b32_e32 v58, 16, v61
	v_and_b32_e32 v59, 0xffff0000, v61
	v_exp_f32_e32 v2, v2
	v_exp_f32_e32 v60, v60
	s_mov_b32 s100, 0x9f5d000
	v_lshl_add_u64 v[22:23], v[20:21], 0, s[100:101]
	global_load_dwordx4 v[36:39], v[22:23], off offset:1024
	v_exp_f32_e32 v61, v46
	v_mul_f32_e32 v46, 0xbfb8aa3b, v72
	v_fmamk_f32 v47, v47, 0xbdd2d3e7, v93
	v_pk_mul_f32 v[70:71], v[0:1], v[44:45] op_sel_hi:[0,1]
	v_pk_mul_f32 v[44:45], v[58:59], v[58:59]
	v_exp_f32_e32 v75, v46
	v_mul_f32_e32 v46, 0xbfb8aa3b, v76
	v_mul_f32_e32 v47, v47, v57
	v_exp_f32_e32 v46, v46
	v_exp_f32_e32 v47, v47
	v_mul_f32_e32 v72, 0xbfb8aa3b, v73
	v_fmamk_f32 v44, v44, 0xbdd2d3e7, v93
	v_exp_f32_e32 v76, v72
	v_mul_f32_e32 v72, 0xbfb8aa3b, v77
	v_mul_f32_e32 v44, v44, v58
	v_exp_f32_e32 v72, v72
	v_exp_f32_e32 v73, v44
	v_mul_f32_e32 v44, 0xbfb8aa3b, v74
	v_fmamk_f32 v45, v45, 0xbdd2d3e7, v93
	v_add_f32_e32 v2, 1.0, v2
	v_pk_add_f32 v[60:61], v[60:61], 1.0 op_sel_hi:[1,0]
	v_exp_f32_e32 v77, v44
	v_mul_f32_e32 v44, 0xbfb8aa3b, v78
	v_mul_f32_e32 v45, v45, v59
	v_rcp_f32_e32 v74, v2
	v_mul_f32_e32 v2, v60, v61
	v_exp_f32_e32 v44, v44
	v_exp_f32_e32 v45, v45
	v_rcp_f32_e32 v60, v2
	v_add_f32_e32 v2, 1.0, v75
	v_pk_add_f32 v[46:47], v[46:47], 1.0 op_sel_hi:[1,0]
	v_rcp_f32_e32 v75, v2
	v_mul_f32_e32 v2, v46, v47
	v_rcp_f32_e32 v61, v2
	v_add_f32_e32 v2, 1.0, v76
	v_pk_add_f32 v[46:47], v[72:73], 1.0 op_sel_hi:[1,0]
	v_cvt_pk_bf16_f32 v62, v62, v63
	v_cvt_pk_bf16_f32 v63, v64, v65
	v_rcp_f32_e32 v76, v2
	v_mul_f32_e32 v2, v46, v47
	v_mov_b64_e32 v[240:241], v[62:63]
	s_nop 1
	v_permlane16_swap_b32_e32 v238, v240
	v_permlane16_swap_b32_e32 v239, v241
	global_store_dwordx4 v[158:159], v[238:241], off
	ds_read_b128 v[62:65], v1 offset:128
	v_rcp_f32_e32 v72, v2
	v_add_f32_e32 v2, 1.0, v77
	v_pk_add_f32 v[44:45], v[44:45], 1.0 op_sel_hi:[1,0]
	v_rcp_f32_e32 v77, v2
	v_mul_f32_e32 v2, v44, v45
	v_rcp_f32_e32 v73, v2
	ds_read_b128 v[44:47], v1 offset:192
	s_waitcnt lgkmcnt(1)
	v_pk_mul_f32 v[58:59], v[64:65], v[58:59]
	v_pk_mul_f32 v[56:57], v[62:63], v[56:57]
	v_pk_mul_f32 v[58:59], v[72:73], v[58:59]
	v_pk_mul_f32 v[56:57], v[60:61], v[56:57]
	v_pk_fma_f32 v[58:59], v[76:77], v[66:67], v[58:59]
	v_pk_fma_f32 v[56:57], v[74:75], v[70:71], v[56:57]
	v_pk_mul_f32 v[42:43], v[0:1], v[42:43] op_sel_hi:[0,1]
	v_pk_mul_f32 v[0:1], v[0:1], v[40:41] op_sel_hi:[0,1]
	v_lshlrev_b32_e32 v40, 16, v54
	s_mov_b32 s100, s66
	v_lshl_add_u64 v[32:33], v[20:21], 0, s[100:101]
	global_load_dwordx4 v[32:35], v[32:33], off
	v_and_b32_e32 v41, 0xffff0000, v54
	v_cvt_pk_bf16_f32 v56, v56, v57
	v_cvt_pk_bf16_f32 v57, v58, v59
	v_lshlrev_b32_e32 v2, 16, v48
	v_and_b32_e32 v58, 0xffff0000, v48
	v_lshlrev_b32_e32 v59, 16, v49
	v_and_b32_e32 v60, 0xffff0000, v49
	v_lshlrev_b32_e32 v48, 16, v55
	v_and_b32_e32 v49, 0xffff0000, v55
	v_pk_mul_f32 v[54:55], v[40:41], v[40:41]
	v_mov_b64_e32 v[242:243], v[56:57]
	v_lshlrev_b32_e32 v56, 16, v50
	v_fmamk_f32 v54, v54, 0xbdd2d3e7, v93
	v_mul_f32_e32 v2, 0xbfb8aa3b, v2
	v_mul_f32_e32 v56, 0xbfb8aa3b, v56
	v_mul_f32_e32 v54, v54, v40
	v_and_b32_e32 v61, 0xffff0000, v50
	v_exp_f32_e32 v2, v2
	v_exp_f32_e32 v56, v56
	v_exp_f32_e32 v57, v54
	v_mul_f32_e32 v54, 0xbfb8aa3b, v58
	v_fmamk_f32 v55, v55, 0xbdd2d3e7, v93
	v_lshlrev_b32_e32 v62, 16, v51
	v_and_b32_e32 v63, 0xffff0000, v51
	v_pk_mul_f32 v[50:51], v[48:49], v[48:49]
	v_exp_f32_e32 v64, v54
	v_mul_f32_e32 v54, 0xbfb8aa3b, v61
	v_mul_f32_e32 v55, v55, v41
	v_exp_f32_e32 v54, v54
	v_exp_f32_e32 v55, v55
	v_mul_f32_e32 v58, 0xbfb8aa3b, v59
	v_fmamk_f32 v50, v50, 0xbdd2d3e7, v93
	v_exp_f32_e32 v65, v58
	v_mul_f32_e32 v58, 0xbfb8aa3b, v62
	v_mul_f32_e32 v50, v50, v48
	v_exp_f32_e32 v58, v58
	v_exp_f32_e32 v59, v50
	v_mul_f32_e32 v50, 0xbfb8aa3b, v60
	v_fmamk_f32 v51, v51, 0xbdd2d3e7, v93
	v_add_f32_e32 v2, 1.0, v2
	v_pk_add_f32 v[56:57], v[56:57], 1.0 op_sel_hi:[1,0]
	v_exp_f32_e32 v62, v50
	v_mul_f32_e32 v50, 0xbfb8aa3b, v63
	v_mul_f32_e32 v51, v51, v49
	v_rcp_f32_e32 v60, v2
	s_mov_b32 s100, 0x9f62000
	v_lshl_add_u64 v[20:21], v[20:21], 0, s[100:101]
	global_load_dwordx4 v[20:23], v[20:21], off offset:3072
	v_mul_f32_e32 v2, v56, v57
	v_exp_f32_e32 v50, v50
	v_exp_f32_e32 v51, v51
	v_rcp_f32_e32 v56, v2
	v_add_f32_e32 v2, 1.0, v64
	v_pk_add_f32 v[54:55], v[54:55], 1.0 op_sel_hi:[1,0]
	v_rcp_f32_e32 v61, v2
	v_mul_f32_e32 v2, v54, v55
	v_rcp_f32_e32 v57, v2
	v_add_f32_e32 v2, 1.0, v65
	v_pk_add_f32 v[58:59], v[58:59], 1.0 op_sel_hi:[1,0]
	v_rcp_f32_e32 v54, v2
	v_mul_f32_e32 v2, v58, v59
	v_rcp_f32_e32 v58, v2
	v_add_f32_e32 v2, 1.0, v62
	v_pk_add_f32 v[50:51], v[50:51], 1.0 op_sel_hi:[1,0]
	v_rcp_f32_e32 v55, v2
	v_mul_f32_e32 v2, v50, v51
	v_rcp_f32_e32 v59, v2
	s_waitcnt lgkmcnt(0)
	v_pk_mul_f32 v[46:47], v[46:47], v[48:49]
	v_pk_mul_f32 v[40:41], v[44:45], v[40:41]
	s_addk_i32 s38, 0x80
	v_pk_mul_f32 v[40:41], v[56:57], v[40:41]
	v_pk_mul_f32 v[44:45], v[58:59], v[46:47]
	v_pk_fma_f32 v[0:1], v[60:61], v[0:1], v[40:41]
	v_pk_fma_f32 v[42:43], v[54:55], v[42:43], v[44:45]
	v_cvt_pk_bf16_f32 v0, v0, v1
	v_cvt_pk_bf16_f32 v1, v42, v43
	v_mov_b64_e32 v[244:245], v[0:1]
	s_nop 1
	v_permlane16_swap_b32_e32 v242, v244
	v_permlane16_swap_b32_e32 v243, v245
	global_store_dwordx4 v[158:159], v[242:245], off offset:64
	s_waitcnt lgkmcnt(0)
	s_barrier
	s_add_u32 s54, s54, 0x160000
	s_addc_u32 s55, s55, 0
	s_cmp_eq_u32 s54, 0x1600000
	s_cbranch_scc1 .LBB0_281
.LBB0_209:
	v_mov_b32_e32 v0, v52
	v_readlane_b32 s0, v255, 8
	v_and_b32_e32 v101, 15, v0
	v_lshlrev_b32_e32 v104, 3, v0
	v_bfe_u32 v88, v0, 4, 2
	v_lshrrev_b32_e32 v1, 2, v0
	v_and_b32_e32 v54, 56, v104
	v_ashrrev_i32_e32 v48, 3, v0
	v_add_u32_e32 v0, 0x200, v0
	v_or_b32_e32 v90, s34, v101
	v_or_b32_e32 v2, s0, v54
	v_ashrrev_i32_e32 v57, 3, v0
	v_mul_lo_u32 v0, v90, s60
	v_readlane_b32 s0, v255, 9
	s_and_b32 s41, s40, 1
	v_lshlrev_b32_e32 v91, 4, v88
	v_add_lshl_u32 v56, v0, s0, 1
	s_add_u32 s0, s39, s54
	v_or_b32_e32 v50, 0x400, v2
	v_or_b32_e32 v59, 0x500, v2
	v_or_b32_e32 v2, v56, v91
	s_addc_u32 s1, s78, s55
	v_and_or_b32 v55, v1, 14, s34
	v_lshl_add_u64 v[0:1], s[0:1], 0, v[2:3]
	v_add_co_u32_e32 v0, vcc, s63, v0
	s_lshl_b32 s8, s41, 7
	s_nop 0
	v_addc_co_u32_e32 v1, vcc, 0, v1, vcc
	global_load_dwordx4 v[44:47], v[0:1], off
	global_load_dwordx4 v[40:43], v[0:1], off offset:64
	v_lshl_add_u32 v0, v54, 1, 0
	v_add_u32_e32 v1, s8, v48
	v_mul_lo_u32 v51, v48, s60
	v_mad_u64_u32 v[48:49], s[6:7], v1, s61, v[0:1]
	v_add_u32_e32 v1, s8, v57
	v_mad_u64_u32 v[0:1], s[6:7], v1, s61, v[0:1]
	v_lshlrev_b32_e32 v1, 2, v54
	s_cmp_eq_u32 s54, 0
	v_mul_lo_u32 v58, v57, s60
	v_add_u32_e32 v57, 0, v1
	s_cselect_b64 s[6:7], -1, 0
	s_add_i32 s10, 0, 0x1f000
	v_cmp_gt_i32_e32 vcc, 3, v55
	ds_write_b128 v48, v[4:7]
	ds_write_b128 v0, v[8:11]
	v_add_lshl_u32 v70, v50, v58, 1
	v_add_lshl_u32 v72, v59, v58, 1
	ds_write_b128 v48, v[12:15] offset:36864
	ds_write_b128 v0, v[16:19] offset:36864
	v_add_u32_e32 v0, 0x1f400, v57
	v_add_u32_e32 v58, s10, v1
	s_and_b64 s[8:9], s[6:7], vcc
	v_cmp_gt_i32_e32 vcc, 2, v55
	ds_read_b128 v[4:7], v0
	ds_read_b128 v[8:11], v0 offset:16
	s_waitcnt vmcnt(8)
	v_cndmask_b32_e64 v64, v31, 0, s[8:9]
	v_cndmask_b32_e64 v65, v30, 0, s[8:9]
	v_cndmask_b32_e64 v66, v29, 0, s[8:9]
	v_cndmask_b32_e64 v63, v28, 0, s[8:9]
	ds_read_b128 v[12:15], v58
	ds_read_b128 v[16:19], v58 offset:16
	s_and_b64 s[8:9], s[6:7], vcc
	v_cmp_gt_i32_e32 vcc, 1, v55
	s_waitcnt vmcnt(7)
	v_cndmask_b32_e64 v67, v27, 0, s[8:9]
	v_cndmask_b32_e64 v68, v26, 0, s[8:9]
	v_cndmask_b32_e64 v69, v25, 0, s[8:9]
	v_cndmask_b32_e64 v71, v24, 0, s[8:9]
	ds_read_b128 v[24:27], v58 offset:256
	ds_read_b128 v[28:31], v58 offset:272
	s_and_b64 s[8:9], s[6:7], vcc
	v_add_lshl_u32 v2, v50, v51, 1
	v_add_lshl_u32 v0, v59, v51, 1
	s_waitcnt vmcnt(6)
	v_cndmask_b32_e64 v73, v39, 0, s[8:9]
	v_cndmask_b32_e64 v89, v38, 0, s[8:9]
	v_cndmask_b32_e64 v83, v37, 0, s[8:9]
	v_cndmask_b32_e64 v77, v36, 0, s[8:9]
	ds_read_b128 v[36:39], v58 offset:512
	ds_read_b128 v[48:51], v58 offset:528
	v_lshlrev_b32_e32 v62, 16, v63
	v_and_b32_e32 v63, 0xffff0000, v63
	s_waitcnt lgkmcnt(5)
	v_pk_fma_f32 v[62:63], v[12:13], v[62:63], v[4:5]
	v_lshlrev_b32_e32 v74, 16, v71
	v_and_b32_e32 v75, 0xffff0000, v71
	s_waitcnt lgkmcnt(3)
	v_pk_fma_f32 v[62:63], v[24:25], v[74:75], v[62:63]
	v_lshlrev_b32_e32 v76, 16, v77
	v_and_b32_e32 v77, 0xffff0000, v77
	s_waitcnt lgkmcnt(1)
	v_pk_fma_f32 v[36:37], v[36:37], v[76:77], v[62:63]
	v_lshlrev_b32_e32 v62, 16, v66
	v_and_b32_e32 v63, 0xffff0000, v66
	v_pk_fma_f32 v[62:63], v[14:15], v[62:63], v[6:7]
	v_lshlrev_b32_e32 v80, 16, v69
	v_and_b32_e32 v81, 0xffff0000, v69
	v_pk_fma_f32 v[62:63], v[26:27], v[80:81], v[62:63]
	v_lshlrev_b32_e32 v82, 16, v83
	v_and_b32_e32 v83, 0xffff0000, v83
	v_pk_fma_f32 v[38:39], v[38:39], v[82:83], v[62:63]
	v_lshlrev_b32_e32 v62, 16, v65
	v_and_b32_e32 v63, 0xffff0000, v65
	v_pk_fma_f32 v[62:63], v[16:17], v[62:63], v[8:9]
	v_lshlrev_b32_e32 v86, 16, v68
	v_and_b32_e32 v87, 0xffff0000, v68
	v_pk_fma_f32 v[62:63], v[28:29], v[86:87], v[62:63]
	v_lshlrev_b32_e32 v102, 16, v89
	v_and_b32_e32 v103, 0xffff0000, v89
	s_waitcnt lgkmcnt(0)
	v_pk_fma_f32 v[48:49], v[48:49], v[102:103], v[62:63]
	v_lshlrev_b32_e32 v62, 16, v64
	v_and_b32_e32 v63, 0xffff0000, v64
	v_pk_fma_f32 v[62:63], v[18:19], v[62:63], v[10:11]
	v_lshlrev_b32_e32 v108, 16, v67
	v_and_b32_e32 v109, 0xffff0000, v67
	s_and_b64 s[8:9], s[80:81], s[6:7]
	v_pk_fma_f32 v[62:63], v[30:31], v[108:109], v[62:63]
	v_lshlrev_b32_e32 v110, 16, v73
	v_and_b32_e32 v111, 0xffff0000, v73
	v_add_u32_e32 v57, 0x1f200, v57
	s_waitcnt vmcnt(4)
	v_cndmask_b32_e64 v105, v35, 0, s[8:9]
	v_cndmask_b32_e64 v107, v34, 0, s[8:9]
	v_cndmask_b32_e64 v85, v33, 0, s[8:9]
	v_cndmask_b32_e64 v79, v32, 0, s[8:9]
	ds_read_b128 v[32:35], v58 offset:768
	ds_read_b128 v[58:61], v58 offset:784
	v_pk_fma_f32 v[50:51], v[50:51], v[110:111], v[62:63]
	ds_read_b128 v[62:65], v57
	ds_read_b128 v[66:69], v57 offset:16
	v_cmp_gt_i32_e32 vcc, -1, v55
	s_and_b64 s[6:7], s[6:7], vcc
	v_pk_fma_f32 v[4:5], v[12:13], v[74:75], v[4:5]
	v_lshlrev_b32_e32 v78, 16, v79
	v_and_b32_e32 v79, 0xffff0000, v79
	s_waitcnt vmcnt(3)
	v_cndmask_b32_e64 v20, v20, 0, s[6:7]
	v_pk_fma_f32 v[4:5], v[24:25], v[76:77], v[4:5]
	v_pk_fma_f32 v[10:11], v[18:19], v[108:109], v[10:11]
	v_pk_fma_f32 v[8:9], v[16:17], v[86:87], v[8:9]
	v_pk_fma_f32 v[6:7], v[14:15], v[80:81], v[6:7]
	s_waitcnt lgkmcnt(1)
	v_pk_fma_f32 v[4:5], v[62:63], v[78:79], v[4:5]
	v_lshlrev_b32_e32 v12, 16, v20
	v_and_b32_e32 v13, 0xffff0000, v20
	v_lshlrev_b32_e32 v84, 16, v85
	v_and_b32_e32 v85, 0xffff0000, v85
	v_lshlrev_b32_e32 v106, 16, v107
	v_and_b32_e32 v107, 0xffff0000, v107
	v_lshlrev_b32_e32 v112, 16, v105
	v_and_b32_e32 v113, 0xffff0000, v105
	v_cndmask_b32_e64 v21, v21, 0, s[6:7]
	v_cndmask_b32_e64 v22, v22, 0, s[6:7]
	v_cndmask_b32_e64 v23, v23, 0, s[6:7]
	v_pk_fma_f32 v[10:11], v[30:31], v[110:111], v[10:11]
	v_pk_fma_f32 v[8:9], v[28:29], v[102:103], v[8:9]
	v_pk_fma_f32 v[6:7], v[26:27], v[82:83], v[6:7]
	v_pk_fma_f32 v[4:5], v[32:33], v[12:13], v[4:5]
	v_mul_lo_u32 v12, v55, s64
	v_pk_fma_f32 v[36:37], v[32:33], v[78:79], v[36:37]
	v_pk_fma_f32 v[38:39], v[34:35], v[84:85], v[38:39]
	s_waitcnt lgkmcnt(0)
	v_pk_fma_f32 v[10:11], v[68:69], v[112:113], v[10:11]
	v_lshlrev_b32_e32 v18, 16, v23
	v_and_b32_e32 v19, 0xffff0000, v23
	v_pk_fma_f32 v[8:9], v[66:67], v[106:107], v[8:9]
	v_lshlrev_b32_e32 v16, 16, v22
	v_and_b32_e32 v17, 0xffff0000, v22
	v_pk_fma_f32 v[6:7], v[64:65], v[84:85], v[6:7]
	v_lshlrev_b32_e32 v14, 16, v21
	v_and_b32_e32 v15, 0xffff0000, v21
	v_add3_u32 v1, s65, v12, v1
	v_pk_fma_f32 v[48:49], v[58:59], v[106:107], v[48:49]
	v_pk_fma_f32 v[50:51], v[60:61], v[112:113], v[50:51]
	v_pk_fma_f32 v[10:11], v[60:61], v[18:19], v[10:11]
	v_pk_fma_f32 v[8:9], v[58:59], v[16:17], v[8:9]
	v_pk_fma_f32 v[6:7], v[34:35], v[14:15], v[6:7]
	ds_write_b128 v1, v[36:39]
	ds_write_b128 v1, v[48:51] offset:16
	ds_write_b128 v1, v[4:7] offset:272
	ds_write_b128 v1, v[8:11] offset:288
	v_lshl_add_u64 v[4:5], s[0:1], 0, v[2:3]
	v_add_co_u32_e32 v4, vcc, s66, v4
	v_mov_b32_e32 v71, v3
	s_nop 0
	v_addc_co_u32_e32 v5, vcc, 0, v5, vcc
	v_lshl_add_u64 v[6:7], s[0:1], 0, v[70:71]
	v_add_co_u32_e32 v8, vcc, s66, v6
	v_mov_b32_e32 v1, v3
	s_nop 0
	v_addc_co_u32_e32 v9, vcc, 0, v7, vcc
	v_lshl_add_u64 v[0:1], s[0:1], 0, v[0:1]
	v_add_co_u32_e32 v0, vcc, s66, v0
	v_mov_b32_e32 v73, v3
	s_nop 0
	v_addc_co_u32_e32 v1, vcc, 0, v1, vcc
	v_lshl_add_u64 v[12:13], s[0:1], 0, v[72:73]
	v_add_co_u32_e32 v16, vcc, s66, v12
	global_load_dwordx4 v[4:7], v[4:5], off
	s_nop 0
	global_load_dwordx4 v[8:11], v[8:9], off
	v_addc_co_u32_e32 v17, vcc, 0, v13, vcc
	global_load_dwordx4 v[12:15], v[0:1], off
	s_nop 0
	global_load_dwordx4 v[16:19], v[16:17], off
	v_mul_lo_u32 v0, v90, s64
	v_add_u32_e32 v102, s65, v0
	s_waitcnt lgkmcnt(0)
	v_lshl_add_u32 v0, v88, 5, v102
	ds_read_b128 v[20:23], v0
	ds_read_b128 v[24:27], v0 offset:16
	v_mul_u32_u24_e32 v1, 0x48, v101
	v_lshlrev_b32_e32 v1, 1, v1
	v_readlane_b32 s0, v254, 49
	s_waitcnt lgkmcnt(1)
	v_cvt_pk_bf16_f32 v20, v20, v21
	v_cvt_pk_bf16_f32 v21, v22, v23
	v_add3_u32 v2, s0, v91, v1
	v_readlane_b32 s0, v254, 52
	s_waitcnt lgkmcnt(0)
	v_cvt_pk_bf16_f32 v22, v24, v25
	v_cvt_pk_bf16_f32 v23, v26, v27
	ds_read_b128 v[24:27], v2
	ds_read_b128 v[28:31], v2 offset:64
	v_add3_u32 v1, s0, v91, v1
	ds_read_b128 v[32:35], v1
	ds_read_b128 v[36:39], v1 offset:64
	ds_read_b128 v[48:51], v2 offset:2304
	ds_read_b128 v[58:61], v2 offset:2368
	ds_read_b128 v[62:65], v1 offset:2304
	ds_read_b128 v[66:69], v1 offset:2368
	ds_read_b128 v[70:73], v2 offset:4608
	ds_read_b128 v[74:77], v2 offset:4672
	ds_read_b128 v[78:81], v1 offset:4608
	ds_read_b128 v[82:85], v1 offset:4672
	ds_read_b128 v[106:109], v2 offset:6912
	ds_read_b128 v[110:113], v1 offset:6912
	ds_read_b128 v[114:117], v2 offset:6976
	ds_read_b128 v[118:121], v0 offset:128
	ds_read_b128 v[122:125], v0 offset:144
	ds_read_b128 v[126:129], v1 offset:6976
	s_waitcnt lgkmcnt(14)
	v_mfma_f32_16x16x32_bf16 v[24:27], v[20:23], v[24:27], 0
	v_lshlrev_b32_e32 v103, 2, v88
	v_or_b32_e32 v105, s34, v103
	v_or_b32_e32 v0, s40, v88
	v_mfma_f32_16x16x32_bf16 v[32:35], v[20:23], v[32:35], 0
	v_lshlrev_b32_e32 v89, 2, v101
	v_cmp_eq_u32_e32 vcc, 0, v0
	v_add_u32_e32 v2, s10, v89
	s_waitcnt lgkmcnt(13)
	v_mfma_f32_16x16x32_bf16 v[48:51], v[20:23], v[48:51], 0
	v_add_u32_e32 v0, s65, v89
	v_readlane_b32 s6, v255, 14
	v_readlane_b32 s7, v255, 15
	s_waitcnt lgkmcnt(11)
	v_mfma_f32_16x16x32_bf16 v[62:65], v[20:23], v[62:65], 0
	s_and_b64 s[6:7], s[6:7], vcc
	v_readlane_b32 s8, v255, 16
	v_cmp_eq_u32_e64 s[0:1], 0, v88
	s_waitcnt lgkmcnt(9)
	v_mfma_f32_16x16x32_bf16 v[70:73], v[20:23], v[70:73], 0
	s_waitcnt lgkmcnt(7)
	v_mfma_f32_16x16x32_bf16 v[78:81], v[20:23], v[78:81], 0
	s_waitcnt lgkmcnt(5)
	v_mfma_f32_16x16x32_bf16 v[106:109], v[20:23], v[106:109], 0
	s_waitcnt lgkmcnt(4)
	v_mfma_f32_16x16x32_bf16 v[20:23], v[20:23], v[110:113], 0
	s_waitcnt lgkmcnt(2)
	v_cvt_pk_bf16_f32 v110, v118, v119
	v_cvt_pk_bf16_f32 v111, v120, v121
	s_waitcnt lgkmcnt(1)
	v_cvt_pk_bf16_f32 v112, v122, v123
	v_cvt_pk_bf16_f32 v113, v124, v125
	s_nop 1
	v_mfma_f32_16x16x32_bf16 v[118:121], v[110:113], v[28:31], v[24:27]
	v_mfma_f32_16x16x32_bf16 v[122:125], v[110:113], v[36:39], v[32:35]
	v_mfma_f32_16x16x32_bf16 v[48:51], v[110:113], v[58:61], v[48:51]
	v_mul_lo_u32 v58, v105, s64
	v_add_u32_e32 v59, 0x110, v58
	v_add_u32_e32 v60, 0x220, v58
	v_add_u32_e32 v61, 0x330, v58
	v_mfma_f32_16x16x32_bf16 v[36:39], v[110:113], v[66:69], v[62:65]
	v_add_u32_e32 v57, v0, v59
	v_mfma_f32_16x16x32_bf16 v[32:35], v[110:113], v[74:77], v[70:73]
	v_add_u32_e32 v76, v0, v60
	v_add_u32_e32 v77, v0, v61
	v_mfma_f32_16x16x32_bf16 v[24:27], v[110:113], v[114:117], v[106:109]
	s_nop 2
	v_add_u32_e32 v106, v0, v58
	ds_read2st64_b32 v[0:1], v2 offset0:5 offset1:6
	ds_read_b32 v2, v2 offset:1792
	ds_read_b32 v62, v106
	ds_read_b32 v63, v57
	ds_read_b32 v64, v76
	ds_read_b32 v65, v77
	s_waitcnt lgkmcnt(5)
	v_fmamk_f32 v67, v122, 0xbfb8aa3b, v1
	v_fmamk_f32 v68, v119, 0xbfb8aa3b, v0
	v_exp_f32_e32 v67, v67
	v_exp_f32_e32 v69, v68
	v_fmamk_f32 v68, v123, 0xbfb8aa3b, v1
	v_exp_f32_e32 v70, v68
	v_fmamk_f32 v66, v118, 0xbfb8aa3b, v0
	v_add_f32_e32 v67, 1.0, v67
	v_exp_f32_e32 v66, v66
	v_rcp_f32_e32 v68, v67
	v_add_f32_e32 v67, 1.0, v69
	v_add_f32_e32 v69, 1.0, v70
	v_fmamk_f32 v70, v120, 0xbfb8aa3b, v0
	v_fmamk_f32 v0, v121, 0xbfb8aa3b, v0
	v_exp_f32_e32 v70, v70
	v_fmamk_f32 v71, v124, 0xbfb8aa3b, v1
	v_exp_f32_e32 v0, v0
	v_exp_f32_e32 v71, v71
	v_add_f32_e32 v66, 1.0, v66
	v_rcp_f32_e32 v66, v66
	v_rcp_f32_e32 v67, v67
	v_add_f32_e32 v70, 1.0, v70
	v_add_f32_e32 v0, 1.0, v0
	v_rcp_f32_e32 v70, v70
	v_add_f32_e32 v72, 1.0, v71
	v_rcp_f32_e32 v71, v0
	v_fmac_f32_e32 v1, 0xbfb8aa3b, v125
	s_waitcnt lgkmcnt(4)
	v_pk_mul_f32 v[66:67], v[2:3], v[66:67] op_sel_hi:[0,1]
	v_exp_f32_e32 v73, v1
	v_pk_mul_f32 v[0:1], v[2:3], v[70:71] op_sel_hi:[0,1]
	v_exp_f32_e32 v74, v66
	v_exp_f32_e32 v75, v67
	v_exp_f32_e32 v0, v0
	v_exp_f32_e32 v1, v1
	v_add_f32_e32 v2, 1.0, v73
	v_pk_mul_f32 v[70:71], v[74:75], v[74:75]
	v_rcp_f32_e32 v73, v2
	v_pk_mul_f32 v[66:67], v[0:1], v[0:1]
	v_sub_f32_e32 v2, 1.0, v70
	v_sqrt_f32_e32 v2, v2
	v_sub_f32_e32 v70, 1.0, v71
	v_sub_f32_e32 v66, 1.0, v66
	v_sub_f32_e32 v67, 1.0, v67
	v_rcp_f32_e32 v69, v69
	v_rcp_f32_e32 v72, v72
	v_sqrt_f32_e32 v71, v70
	v_sqrt_f32_e32 v66, v66
	v_sqrt_f32_e32 v67, v67
	v_cndmask_b32_e64 v70, v2, 1.0, s[6:7]
	v_pk_mul_f32 v[68:69], v[68:69], v[70:71]
	v_mfma_f32_16x16x32_bf16 v[28:31], v[110:113], v[82:85], v[78:81]
	v_mul_f32_e64 v66, v72, v66
	v_mul_f32_e64 v67, v73, v67
	s_waitcnt lgkmcnt(0)
	v_pk_mul_f32 v[64:65], v[64:65], v[66:67]
	v_pk_mul_f32 v[66:67], v[62:63], v[68:69]
	ds_write_b32 v57, v67
	v_fma_f32 v2, 0, v74, v66
	v_fmac_f32_e32 v67, v75, v2
	v_mul_f32_e32 v2, v75, v74
	v_and_or_b32 v78, v95, 64, v101
	v_fma_f32 v57, v0, v67, v64
	v_mul_f32_e32 v2, v0, v2
	ds_write_b32 v77, v65
	v_fmac_f32_e32 v65, v1, v57
	v_mul_f32_e32 v57, v1, v2
	v_lshlrev_b32_e32 v2, 2, v78
	ds_bpermute_b32 v122, v2, v57
	ds_bpermute_b32 v136, v2, v65
	ds_bpermute_b32 v123, v2, v57 offset:64
	ds_bpermute_b32 v132, v2, v65 offset:64
	ds_bpermute_b32 v120, v2, v57 offset:128
	ds_bpermute_b32 v131, v2, v65 offset:128
	ds_bpermute_b32 v62, v2, v57 offset:192
	ds_bpermute_b32 v63, v2, v65 offset:192
	v_mfma_f32_16x16x32_bf16 v[20:23], v[110:113], v[126:129], v[20:23]
	s_waitcnt lgkmcnt(6)
	v_fmac_f32_e32 v136, 0, v122
	v_lshl_add_u32 v57, v101, 2, s8
	ds_write_b32 v106, v66
	ds_write_b32 v76, v64
	s_and_saveexec_b64 s[8:9], s[0:1]
	s_cbranch_execz .LBB0_211
	s_waitcnt lgkmcnt(7)
	v_mul_f32_e32 v64, v122, v123
	s_waitcnt lgkmcnt(6)
	v_fma_f32 v65, v136, v123, v132
	s_waitcnt lgkmcnt(5)
	v_mul_f32_e32 v64, v64, v120
	s_waitcnt lgkmcnt(4)
	v_fma_f32 v65, v65, v120, v131
	s_waitcnt lgkmcnt(3)
	v_mul_f32_e32 v64, v64, v62
	s_waitcnt lgkmcnt(2)
	v_fmac_f32_e32 v63, v65, v62
	ds_write2st64_b32 v57, v64, v63 offset1:8
